# k39 + Toeplitz tap reduction loop of the P1 operand build software-pipelined by one step (two register sets)
# baseline (speedup 1.0000x reference)
; __global__ void __launch_bounds__(512, 2) hybrid_fwd(Params P) {
;     ...
;                 for (int p = 0; p < 64; ++p) { const float ar = ap[2 * p], ai = ap[2 * p + 1], br = bp[p * 32], bi = bp[p * 32 + 1];
;                     const float wr_ = ar * br - ai * bi, wi_ = ar * bi + ai * br; acc += cr[p] * wr_ - ci[p] * wi_; }
.Lmy_tp_loop:
	v_lshl_add_u64 v[194:195], s[6:7], 0, v[8:9]
	v_add_co_u32_e32 v204, vcc, 0x500000, v194
	v_lshl_add_u64 v[188:189], s[6:7], 0, v[6:7]
	s_nop 0
	v_addc_co_u32_e32 v205, vcc, 0, v195, vcc
	v_lshl_add_u64 v[196:197], v[26:27], 0, s[0:1]
	v_lshl_add_u64 v[198:199], v[10:11], 0, s[0:1]
	v_lshl_add_u64 v[202:203], v[188:189], 0, s[14:15]
	v_add_co_u32_e32 v188, vcc, 0x400000, v188
	global_load_dwordx4 v[180:183], v[196:197], off
	global_load_dwordx4 v[184:187], v[198:199], off
	v_addc_co_u32_e32 v189, vcc, 0, v189, vcc
	global_load_dwordx2 v[206:207], v[204:205], off
	global_load_dwordx4 v[194:197], v[202:203], off offset:16
	global_load_dwordx2 v[208:209], v[204:205], off offset:128
	global_load_dwordx2 v[210:211], v[204:205], off offset:256
	global_load_dwordx4 v[198:201], v[188:189], off
	global_load_dwordx2 v[212:213], v[204:205], off offset:384
	s_add_u32 s0, s0, 16
	s_addc_u32 s1, s1, 0
	v_lshl_add_u64 v[6:7], v[6:7], 0, 32
	v_lshl_add_u64 v[8:9], v[8:9], 0, s[16:17]
	s_waitcnt vmcnt(8)
	v_mov_b32_e32 v38, v30
	v_mov_b32_e32 v39, v34
	v_mov_b32_e32 v34, v31
	v_mov_b32_e32 v30, v32
	v_mov_b32_e32 v31, v36
	v_mov_b32_e32 v36, v33
	v_pk_mul_f32 v[32:33], v[44:45], v[60:61] op_sel:[1,1] op_sel_hi:[0,1]
	v_pk_mul_f32 v[52:53], v[46:47], v[62:63] op_sel:[1,1] op_sel_hi:[0,1]
	v_pk_mul_f32 v[54:55], v[48:49], v[56:57] op_sel:[1,1] op_sel_hi:[0,1]
	v_pk_mul_f32 v[64:65], v[50:51], v[58:59] op_sel:[1,1] op_sel_hi:[0,1]
	v_pk_fma_f32 v[66:67], v[44:45], v[60:61], v[32:33] neg_lo:[0,0,1] neg_hi:[0,0,1]
	v_pk_fma_f32 v[32:33], v[44:45], v[60:61], v[32:33] op_sel_hi:[1,0,1]
	v_pk_fma_f32 v[44:45], v[46:47], v[62:63], v[52:53] neg_lo:[0,0,1] neg_hi:[0,0,1]
	v_pk_fma_f32 v[46:47], v[46:47], v[62:63], v[52:53] op_sel_hi:[1,0,1]
	v_pk_fma_f32 v[52:53], v[48:49], v[56:57], v[54:55] neg_lo:[0,0,1] neg_hi:[0,0,1]
	v_pk_fma_f32 v[48:49], v[48:49], v[56:57], v[54:55] op_sel_hi:[1,0,1]
	v_pk_fma_f32 v[54:55], v[50:51], v[58:59], v[64:65] neg_lo:[0,0,1] neg_hi:[0,0,1]
	v_pk_fma_f32 v[50:51], v[50:51], v[58:59], v[64:65] op_sel_hi:[1,0,1]
	v_mov_b32_e32 v45, v47
	v_mov_b32_e32 v53, v49
	v_mov_b32_e32 v67, v33
	v_mov_b32_e32 v55, v51
	v_pk_mul_f32 v[32:33], v[36:37], v[44:45]
	v_pk_mul_f32 v[36:37], v[38:39], v[52:53]
	v_pk_mul_f32 v[34:35], v[34:35], v[54:55]
	v_sub_f32_e32 v21, v36, v37
	v_pk_mul_f32 v[30:31], v[30:31], v[66:67]
	v_sub_f32_e32 v29, v34, v35
	v_add_f32_e32 v1, v1, v21
	v_sub_f32_e32 v3, v30, v31
	v_add_f32_e32 v1, v1, v29
	v_sub_f32_e32 v5, v32, v33
	v_add_f32_e32 v1, v1, v3
	v_add_f32_e32 v1, v1, v5
	s_cmpk_eq_i32 s0, 0x100
	s_cbranch_scc1 .Lmy_tp_tail
	v_lshl_add_u64 v[44:45], s[6:7], 0, v[8:9]
	v_add_co_u32_e32 v54, vcc, 0x500000, v44
	v_lshl_add_u64 v[38:39], s[6:7], 0, v[6:7]
	s_nop 0
	v_addc_co_u32_e32 v55, vcc, 0, v45, vcc
	v_lshl_add_u64 v[46:47], v[26:27], 0, s[0:1]
	v_lshl_add_u64 v[48:49], v[10:11], 0, s[0:1]
	v_lshl_add_u64 v[52:53], v[38:39], 0, s[14:15]
	v_add_co_u32_e32 v38, vcc, 0x400000, v38
	global_load_dwordx4 v[30:33], v[46:47], off
	global_load_dwordx4 v[34:37], v[48:49], off
	v_addc_co_u32_e32 v39, vcc, 0, v39, vcc
	global_load_dwordx2 v[56:57], v[54:55], off
	global_load_dwordx4 v[44:47], v[52:53], off offset:16
	global_load_dwordx2 v[58:59], v[54:55], off offset:128
	global_load_dwordx2 v[60:61], v[54:55], off offset:256
	global_load_dwordx4 v[48:51], v[38:39], off
	global_load_dwordx2 v[62:63], v[54:55], off offset:384
	s_add_u32 s0, s0, 16
	s_addc_u32 s1, s1, 0
	v_lshl_add_u64 v[6:7], v[6:7], 0, 32
	v_lshl_add_u64 v[8:9], v[8:9], 0, s[16:17]
	s_waitcnt vmcnt(8)
	v_mov_b32_e32 v188, v180
	v_mov_b32_e32 v189, v184
	v_mov_b32_e32 v184, v181
	v_mov_b32_e32 v180, v182
	v_mov_b32_e32 v181, v186
	v_mov_b32_e32 v186, v183
	v_pk_mul_f32 v[182:183], v[194:195], v[210:211] op_sel:[1,1] op_sel_hi:[0,1]
	v_pk_mul_f32 v[202:203], v[196:197], v[212:213] op_sel:[1,1] op_sel_hi:[0,1]
	v_pk_mul_f32 v[204:205], v[198:199], v[206:207] op_sel:[1,1] op_sel_hi:[0,1]
	v_pk_mul_f32 v[214:215], v[200:201], v[208:209] op_sel:[1,1] op_sel_hi:[0,1]
	v_pk_fma_f32 v[216:217], v[194:195], v[210:211], v[182:183] neg_lo:[0,0,1] neg_hi:[0,0,1]
	v_pk_fma_f32 v[182:183], v[194:195], v[210:211], v[182:183] op_sel_hi:[1,0,1]
	v_pk_fma_f32 v[194:195], v[196:197], v[212:213], v[202:203] neg_lo:[0,0,1] neg_hi:[0,0,1]
	v_pk_fma_f32 v[196:197], v[196:197], v[212:213], v[202:203] op_sel_hi:[1,0,1]
	v_pk_fma_f32 v[202:203], v[198:199], v[206:207], v[204:205] neg_lo:[0,0,1] neg_hi:[0,0,1]
	v_pk_fma_f32 v[198:199], v[198:199], v[206:207], v[204:205] op_sel_hi:[1,0,1]
	v_pk_fma_f32 v[204:205], v[200:201], v[208:209], v[214:215] neg_lo:[0,0,1] neg_hi:[0,0,1]
	v_pk_fma_f32 v[200:201], v[200:201], v[208:209], v[214:215] op_sel_hi:[1,0,1]
	v_mov_b32_e32 v195, v197
	v_mov_b32_e32 v203, v199
	v_mov_b32_e32 v217, v183
	v_mov_b32_e32 v205, v201
	v_pk_mul_f32 v[182:183], v[186:187], v[194:195]
	v_pk_mul_f32 v[186:187], v[188:189], v[202:203]
	v_pk_mul_f32 v[184:185], v[184:185], v[204:205]
	v_sub_f32_e32 v21, v186, v187
	v_pk_mul_f32 v[180:181], v[180:181], v[216:217]
	v_sub_f32_e32 v29, v184, v185
	v_add_f32_e32 v1, v1, v21
	v_sub_f32_e32 v3, v180, v181
	v_add_f32_e32 v1, v1, v29
	v_sub_f32_e32 v5, v182, v183
	v_add_f32_e32 v1, v1, v3
	v_add_f32_e32 v1, v1, v5
	s_branch .Lmy_tp_loop
; __device__ __forceinline__ bf16_t f2bf(float f) { return (bf16_t)(cvt_pk_bf16(f, 0.f) & 0xffffu); }
; #define INP(i) ((const float*)ld_ptr(pb, (i)))
; __global__ void __launch_bounds__(512, 2) hybrid_fwd(Params P) {
;     ...
;                 for (int p = 0; p < 64; ++p) { const float ar = ap[2 * p], ai = ap[2 * p + 1], br = bp[p * 32], bi = bp[p * 32 + 1];
;                     const float wr_ = ar * br - ai * bi, wi_ = ar * bi + ai * br; acc += cr[p] * wr_ - ci[p] * wi_; }
;                 if (tau == 0 && c == cp) acc += INP(22)[lg * 16 + c];
;                 const bf16_t v = f2bf(acc);
.Lmy_tp_tail:
	s_waitcnt vmcnt(0)
	v_mov_b32_e32 v188, v180
	v_mov_b32_e32 v189, v184
	v_mov_b32_e32 v184, v181
	v_mov_b32_e32 v180, v182
	v_mov_b32_e32 v181, v186
	v_mov_b32_e32 v186, v183
	v_pk_mul_f32 v[182:183], v[194:195], v[210:211] op_sel:[1,1] op_sel_hi:[0,1]
	v_pk_mul_f32 v[202:203], v[196:197], v[212:213] op_sel:[1,1] op_sel_hi:[0,1]
	v_pk_mul_f32 v[204:205], v[198:199], v[206:207] op_sel:[1,1] op_sel_hi:[0,1]
	v_pk_mul_f32 v[214:215], v[200:201], v[208:209] op_sel:[1,1] op_sel_hi:[0,1]
	v_pk_fma_f32 v[216:217], v[194:195], v[210:211], v[182:183] neg_lo:[0,0,1] neg_hi:[0,0,1]
	v_pk_fma_f32 v[182:183], v[194:195], v[210:211], v[182:183] op_sel_hi:[1,0,1]
	v_pk_fma_f32 v[194:195], v[196:197], v[212:213], v[202:203] neg_lo:[0,0,1] neg_hi:[0,0,1]
	v_pk_fma_f32 v[196:197], v[196:197], v[212:213], v[202:203] op_sel_hi:[1,0,1]
	v_pk_fma_f32 v[202:203], v[198:199], v[206:207], v[204:205] neg_lo:[0,0,1] neg_hi:[0,0,1]
	v_pk_fma_f32 v[198:199], v[198:199], v[206:207], v[204:205] op_sel_hi:[1,0,1]
	v_pk_fma_f32 v[204:205], v[200:201], v[208:209], v[214:215] neg_lo:[0,0,1] neg_hi:[0,0,1]
	v_pk_fma_f32 v[200:201], v[200:201], v[208:209], v[214:215] op_sel_hi:[1,0,1]
	v_mov_b32_e32 v195, v197
	v_mov_b32_e32 v203, v199
	v_mov_b32_e32 v217, v183
	v_mov_b32_e32 v205, v201
	v_pk_mul_f32 v[182:183], v[186:187], v[194:195]
	v_pk_mul_f32 v[186:187], v[188:189], v[202:203]
	v_pk_mul_f32 v[184:185], v[184:185], v[204:205]
	v_sub_f32_e32 v21, v186, v187
	v_pk_mul_f32 v[180:181], v[180:181], v[216:217]
	v_sub_f32_e32 v29, v184, v185
	v_add_f32_e32 v1, v1, v21
	v_sub_f32_e32 v3, v180, v181
	v_add_f32_e32 v1, v1, v29
	v_sub_f32_e32 v5, v182, v183
	v_add_f32_e32 v1, v1, v3
	v_add_f32_e32 v1, v1, v5
	v_cmp_eq_u32_e32 vcc, 0, v20
	v_cmp_eq_u32_e64 s[0:1], v12, v2
	s_and_b64 s[4:5], s[0:1], vcc
	s_and_saveexec_b64 s[0:1], s[4:5]
	s_cbranch_execz .LBB0_181
	ds_read_b64 v[6:7], v13 offset:176
	v_lshl_or_b32 v4, v4, 4, v12
	v_ashrrev_i32_e32 v5, 31, v4
	s_waitcnt lgkmcnt(0)
	v_readfirstlane_b32 s4, v7
	v_readfirstlane_b32 s5, v6
	s_nop 0
	v_mov_b32_e32 v7, s4
	v_mov_b32_e32 v6, s5
	v_lshl_add_u64 v[4:5], v[4:5], 2, v[6:7]
	global_load_dword v3, v[4:5], off
	s_waitcnt vmcnt(0)
	v_add_f32_e32 v1, v1, v3
